# v63: prep phase uses the hand-written block transposer for layer 0's weight copies, cache copies re-dealt off the GEMV workgroups, GEMV 64 loads in flight
# baseline (speedup 1.0000x reference)
.LBB0_17:
	s_load_dwordx8 s[8:15], s[0:1], 0x80
	s_andn2_b64 vcc, exec, s[4:5]
	s_mov_b32 s2, s28
	s_waitcnt lgkmcnt(0)
	v_writelane_b32 v255, s8, 20
	s_nop 1
	v_writelane_b32 v255, s9, 21
	v_writelane_b32 v255, s10, 22
	v_writelane_b32 v255, s11, 23
	v_writelane_b32 v255, s12, 24
	v_writelane_b32 v255, s13, 25
	v_writelane_b32 v255, s14, 26
	v_writelane_b32 v255, s15, 27
	s_cbranch_vccnz .LBB0_19
	v_mov_b32_e32 v5, 0
	s_mov_b32 s2, 1
	v_readfirstlane_b32 s20, v174
	s_lshr_b32 s20, s20, 6
	s_lshl_b32 s21, s59, 3
	s_add_i32 s21, s21, s20
	s_mov_b32 s22, 0
	s_cmpk_lt_u32 s21, 0x180
	s_cbranch_scc1 .Lpt_done
	s_cmpk_lt_u32 s21, 0x400
	s_cselect_b32 s55, 2, 1
	v_and_b32_e32 v102, 63, v174
	v_and_b32_e32 v103, 31, v102
	v_lshrrev_b32_e32 v104, 5, v102
	s_mul_i32 s23, s20, 0x2100
	s_addk_i32 s23, 0x5000
	v_mul_u32_u24_e32 v105, 33, v104
	v_add_u32_e32 v105, v105, v103
	v_lshl_add_u32 v105, v105, 2, s23
	v_and_b32_e32 v106, 7, v102
	v_lshrrev_b32_e32 v107, 3, v102
	v_mul_u32_u24_e32 v108, 0x108, v106
	v_add_u32_e32 v108, v108, v107
	v_lshl_add_u32 v108, v108, 2, s23
	v_lshlrev_b32_e32 v109, 11, v107
	v_lshl_add_u32 v109, v106, 4, v109
	s_mov_b32 s30, 0
.Lpt_item:
	s_cmp_ge_u32 s30, s55
	s_cbranch_scc1 .Lpt_done
	s_cmpk_ge_u32 s21, 0x600
	s_cbranch_scc1 .Lpt_wout
	s_mul_i32 s35, s30, 0x480
	s_add_i32 s35, s35, s21
	s_sub_i32 s35, s35, 0x180
	s_mul_i32 s36, s35, 0x2493
	s_lshr_b32 s36, s36, 20
	s_mul_i32 s37, s36, 0x70
	s_sub_i32 s37, s35, s37
	s_movk_i32 s41, 0xe00
	v_readlane_b32 s44, v255, 6
	v_readlane_b32 s45, v255, 7
	s_mov_b32 s48, 0
	s_branch .Lpt_go
.Lpt_wout:
	s_sub_i32 s35, s21, 0x600
	s_lshr_b32 s36, s35, 5
	s_and_b32 s37, s35, 31
	s_movk_i32 s41, 0x400
	v_readlane_b32 s44, v255, 8
	v_readlane_b32 s45, v255, 9
	s_mov_b32 s48, 0x1c00000
.Lpt_go:
	s_add_u32 s48, s56, s48
	s_addc_u32 s49, s57, 0
	s_lshl_b32 s50, s36, 6
	s_mul_i32 s51, s50, s41
	s_lshl_b32 s53, s37, 5
	s_add_i32 s51, s51, s53
	s_lshl_b32 s51, s51, 2
	s_add_u32 s44, s44, s51
	s_addc_u32 s45, s45, 0
	v_mul_lo_u32 v110, v104, s41
	v_add_u32_e32 v110, v110, v103
	v_lshlrev_b32_e32 v110, 2, v110
	s_lshl_b32 s54, s41, 3
	global_load_dword v132, v110, s[44:45]
	s_add_u32 s44, s44, s54
	s_addc_u32 s45, s45, 0
	global_load_dword v133, v110, s[44:45]
	s_add_u32 s44, s44, s54
	s_addc_u32 s45, s45, 0
	global_load_dword v134, v110, s[44:45]
	s_add_u32 s44, s44, s54
	s_addc_u32 s45, s45, 0
	global_load_dword v135, v110, s[44:45]
	s_add_u32 s44, s44, s54
	s_addc_u32 s45, s45, 0
	global_load_dword v136, v110, s[44:45]
	s_add_u32 s44, s44, s54
	s_addc_u32 s45, s45, 0
	global_load_dword v137, v110, s[44:45]
	s_add_u32 s44, s44, s54
	s_addc_u32 s45, s45, 0
	global_load_dword v138, v110, s[44:45]
	s_add_u32 s44, s44, s54
	s_addc_u32 s45, s45, 0
	global_load_dword v139, v110, s[44:45]
	s_add_u32 s44, s44, s54
	s_addc_u32 s45, s45, 0
	global_load_dword v140, v110, s[44:45]
	s_add_u32 s44, s44, s54
	s_addc_u32 s45, s45, 0
	global_load_dword v141, v110, s[44:45]
	s_add_u32 s44, s44, s54
	s_addc_u32 s45, s45, 0
	global_load_dword v142, v110, s[44:45]
	s_add_u32 s44, s44, s54
	s_addc_u32 s45, s45, 0
	global_load_dword v143, v110, s[44:45]
	s_add_u32 s44, s44, s54
	s_addc_u32 s45, s45, 0
	global_load_dword v144, v110, s[44:45]
	s_add_u32 s44, s44, s54
	s_addc_u32 s45, s45, 0
	global_load_dword v145, v110, s[44:45]
	s_add_u32 s44, s44, s54
	s_addc_u32 s45, s45, 0
	global_load_dword v146, v110, s[44:45]
	s_add_u32 s44, s44, s54
	s_addc_u32 s45, s45, 0
	global_load_dword v147, v110, s[44:45]
	s_add_u32 s44, s44, s54
	s_addc_u32 s45, s45, 0
	global_load_dword v148, v110, s[44:45]
	s_add_u32 s44, s44, s54
	s_addc_u32 s45, s45, 0
	global_load_dword v149, v110, s[44:45]
	s_add_u32 s44, s44, s54
	s_addc_u32 s45, s45, 0
	global_load_dword v150, v110, s[44:45]
	s_add_u32 s44, s44, s54
	s_addc_u32 s45, s45, 0
	global_load_dword v151, v110, s[44:45]
	s_add_u32 s44, s44, s54
	s_addc_u32 s45, s45, 0
	global_load_dword v152, v110, s[44:45]
	s_add_u32 s44, s44, s54
	s_addc_u32 s45, s45, 0
	global_load_dword v153, v110, s[44:45]
	s_add_u32 s44, s44, s54
	s_addc_u32 s45, s45, 0
	global_load_dword v154, v110, s[44:45]
	s_add_u32 s44, s44, s54
	s_addc_u32 s45, s45, 0
	global_load_dword v155, v110, s[44:45]
	s_add_u32 s44, s44, s54
	s_addc_u32 s45, s45, 0
	global_load_dword v156, v110, s[44:45]
	s_add_u32 s44, s44, s54
	s_addc_u32 s45, s45, 0
	global_load_dword v157, v110, s[44:45]
	s_add_u32 s44, s44, s54
	s_addc_u32 s45, s45, 0
	global_load_dword v158, v110, s[44:45]
	s_add_u32 s44, s44, s54
	s_addc_u32 s45, s45, 0
	global_load_dword v159, v110, s[44:45]
	s_add_u32 s44, s44, s54
	s_addc_u32 s45, s45, 0
	global_load_dword v160, v110, s[44:45]
	s_add_u32 s44, s44, s54
	s_addc_u32 s45, s45, 0
	global_load_dword v161, v110, s[44:45]
	s_add_u32 s44, s44, s54
	s_addc_u32 s45, s45, 0
	global_load_dword v162, v110, s[44:45]
	s_add_u32 s44, s44, s54
	s_addc_u32 s45, s45, 0
	global_load_dword v163, v110, s[44:45]
	s_add_u32 s44, s44, s54
	s_addc_u32 s45, s45, 0
	s_lshl_b32 s53, s53, 10
	s_add_i32 s53, s53, s50
	s_lshl_b32 s53, s53, 1
	s_add_u32 s48, s48, s53
	s_addc_u32 s49, s49, 0
	s_waitcnt vmcnt(31)
	ds_write_b32 v105, v132
	s_waitcnt vmcnt(30)
	ds_write_b32 v105, v133 offset:264
	s_waitcnt vmcnt(29)
	ds_write_b32 v105, v134 offset:528
	s_waitcnt vmcnt(28)
	ds_write_b32 v105, v135 offset:792
	s_waitcnt vmcnt(27)
	ds_write_b32 v105, v136 offset:1056
	s_waitcnt vmcnt(26)
	ds_write_b32 v105, v137 offset:1320
	s_waitcnt vmcnt(25)
	ds_write_b32 v105, v138 offset:1584
	s_waitcnt vmcnt(24)
	ds_write_b32 v105, v139 offset:1848
	s_waitcnt vmcnt(23)
	ds_write_b32 v105, v140 offset:2112
	s_waitcnt vmcnt(22)
	ds_write_b32 v105, v141 offset:2376
	s_waitcnt vmcnt(21)
	ds_write_b32 v105, v142 offset:2640
	s_waitcnt vmcnt(20)
	ds_write_b32 v105, v143 offset:2904
	s_waitcnt vmcnt(19)
	ds_write_b32 v105, v144 offset:3168
	s_waitcnt vmcnt(18)
	ds_write_b32 v105, v145 offset:3432
	s_waitcnt vmcnt(17)
	ds_write_b32 v105, v146 offset:3696
	s_waitcnt vmcnt(16)
	ds_write_b32 v105, v147 offset:3960
	s_waitcnt vmcnt(15)
	ds_write_b32 v105, v148 offset:4224
	s_waitcnt vmcnt(14)
	ds_write_b32 v105, v149 offset:4488
	s_waitcnt vmcnt(13)
	ds_write_b32 v105, v150 offset:4752
	s_waitcnt vmcnt(12)
	ds_write_b32 v105, v151 offset:5016
	s_waitcnt vmcnt(11)
	ds_write_b32 v105, v152 offset:5280
	s_waitcnt vmcnt(10)
	ds_write_b32 v105, v153 offset:5544
	s_waitcnt vmcnt(9)
	ds_write_b32 v105, v154 offset:5808
	s_waitcnt vmcnt(8)
	ds_write_b32 v105, v155 offset:6072
	s_waitcnt vmcnt(7)
	ds_write_b32 v105, v156 offset:6336
	s_waitcnt vmcnt(6)
	ds_write_b32 v105, v157 offset:6600
	s_waitcnt vmcnt(5)
	ds_write_b32 v105, v158 offset:6864
	s_waitcnt vmcnt(4)
	ds_write_b32 v105, v159 offset:7128
	s_waitcnt vmcnt(3)
	ds_write_b32 v105, v160 offset:7392
	s_waitcnt vmcnt(2)
	ds_write_b32 v105, v161 offset:7656
	s_waitcnt vmcnt(1)
	ds_write_b32 v105, v162 offset:7920
	s_waitcnt vmcnt(0)
	ds_write_b32 v105, v163 offset:8184
	s_waitcnt lgkmcnt(0)
	ds_read2_b32 v[164:165], v108 offset0:0 offset1:33
	ds_read2_b32 v[166:167], v108 offset0:66 offset1:99
	ds_read2_b32 v[168:169], v108 offset0:132 offset1:165
	ds_read2_b32 v[170:171], v108 offset0:198 offset1:231
	s_waitcnt lgkmcnt(0)
	v_cvt_pk_bf16_f32 v96, v164, v165
	v_cvt_pk_bf16_f32 v97, v166, v167
	v_cvt_pk_bf16_f32 v98, v168, v169
	v_cvt_pk_bf16_f32 v99, v170, v171
	global_store_dwordx4 v109, v[96:99], s[48:49]
	s_add_u32 s48, s48, 0x4000
	s_addc_u32 s49, s49, 0
	ds_read2_b32 v[164:165], v108 offset0:8 offset1:41
	ds_read2_b32 v[166:167], v108 offset0:74 offset1:107
	ds_read2_b32 v[168:169], v108 offset0:140 offset1:173
	ds_read2_b32 v[170:171], v108 offset0:206 offset1:239
	s_waitcnt lgkmcnt(0)
	v_cvt_pk_bf16_f32 v96, v164, v165
	v_cvt_pk_bf16_f32 v97, v166, v167
	v_cvt_pk_bf16_f32 v98, v168, v169
	v_cvt_pk_bf16_f32 v99, v170, v171
	global_store_dwordx4 v109, v[96:99], s[48:49]
	s_add_u32 s48, s48, 0x4000
	s_addc_u32 s49, s49, 0
	ds_read2_b32 v[164:165], v108 offset0:16 offset1:49
	ds_read2_b32 v[166:167], v108 offset0:82 offset1:115
	ds_read2_b32 v[168:169], v108 offset0:148 offset1:181
	ds_read2_b32 v[170:171], v108 offset0:214 offset1:247
	s_waitcnt lgkmcnt(0)
	v_cvt_pk_bf16_f32 v96, v164, v165
	v_cvt_pk_bf16_f32 v97, v166, v167
	v_cvt_pk_bf16_f32 v98, v168, v169
	v_cvt_pk_bf16_f32 v99, v170, v171
	global_store_dwordx4 v109, v[96:99], s[48:49]
	s_add_u32 s48, s48, 0x4000
	s_addc_u32 s49, s49, 0
	ds_read2_b32 v[164:165], v108 offset0:24 offset1:57
	ds_read2_b32 v[166:167], v108 offset0:90 offset1:123
	ds_read2_b32 v[168:169], v108 offset0:156 offset1:189
	ds_read2_b32 v[170:171], v108 offset0:222 offset1:255
	s_waitcnt lgkmcnt(0)
	v_cvt_pk_bf16_f32 v96, v164, v165
	v_cvt_pk_bf16_f32 v97, v166, v167
	v_cvt_pk_bf16_f32 v98, v168, v169
	v_cvt_pk_bf16_f32 v99, v170, v171
	global_store_dwordx4 v109, v[96:99], s[48:49]
	s_add_u32 s48, s48, 0x4000
	s_addc_u32 s49, s49, 0
	s_add_i32 s30, s30, 1
	s_branch .Lpt_item
.Lpt_done:
.LBB0_19:
	s_mov_b32 s10, 0
	v_cmp_lt_i32_e32 vcc, 0, v5
	v_lshlrev_b32_e32 v11, 3, v174
	s_and_saveexec_b64 s[0:1], vcc
	s_cbranch_execz .LBB0_30
	s_movk_i32 s4, 0x2100
	v_lshrrev_b32_e32 v7, 3, v2
	v_and_b32_e32 v14, 56, v11
	v_mad_u32_u24 v1, v6, s4, 0
	v_mul_u32_u24_e32 v3, 0x84, v14
	v_lshlrev_b32_e32 v12, 2, v7
	s_add_u32 s4, s56, 0x1c00000
	v_lshrrev_b32_e32 v6, 5, v2
	v_and_b32_e32 v8, 31, v174
	v_add3_u32 v3, v1, v3, v12
	s_addc_u32 s5, s57, 0
	v_mov_b32_e32 v9, 0
	v_lshl_add_u32 v10, v8, 2, v1
	s_movk_i32 s11, 0x84
	v_or_b32_e32 v24, 8, v7
	v_or_b32_e32 v25, 16, v7
	v_or_b32_e32 v26, 24, v7
	v_mov_b32_e32 v1, v6
	s_mov_b64 s[6:7], 0
	s_mov_b32 s12, 0x38e38e39
	s_movk_i32 s13, 0x6ff
	s_mov_b32 s14, 0xe00000
	s_movk_i32 s15, 0x3800
	v_mov_b32_e32 v27, 0x1f200
	v_lshlrev_b32_e32 v12, 2, v8
	v_lshlrev_b32_e32 v14, 1, v14
	v_add_u32_e32 v28, 0x5000, v3
	v_mov_b32_e32 v29, 6
	v_mov_b32_e32 v30, 5
	s_branch .LBB0_22

.LBB0_30:
	s_or_b64 exec, exec, s[0:1]
	v_lshl_add_u32 v1, s59, 9, v174
	v_add_u32_e32 v1, 0xffff0000, v1
	s_mov_b32 s0, 0x10000
	s_lshl_b32 s2, s3, 9
	v_cmp_gt_u32_e32 vcc, s0, v1
	s_and_saveexec_b64 s[0:1], vcc
	s_cbranch_execz .LBB0_35
	s_add_u32 s4, s56, 0xe200000
	s_addc_u32 s5, s57, 0
	v_lshlrev_b32_e32 v3, 3, v1
	s_lshl_b32 s8, s3, 12
	s_mov_b64 s[6:7], 0
	v_mov_b32_e32 v5, 0
	s_mov_b32 s9, 0xffff
	v_mov_b32_e32 v6, v1

.LBB0_35:
	s_or_b64 exec, exec, s[0:1]
	v_lshl_add_u32 v1, s59, 9, v174
	s_lshl_b32 s2, s3, 9
	s_cmpk_gt_i32 s59, 0xcf
	s_cselect_b32 s4, 0x1a000, 0
	s_cselect_b32 s2, 0x1a000, s2
	v_subrev_u32_e32 v1, s4, v1
	s_cmpk_lt_i32 s59, 0x30
	s_cselect_b32 s4, 0x7fffffff, 0
	v_or_b32_e32 v1, s4, v1
	s_mov_b32 s0, 0x20000
	v_cmp_gt_i32_e32 vcc, s0, v1
	s_and_saveexec_b64 s[0:1], vcc
	s_cbranch_execz .LBB0_40
	s_add_u32 s4, s56, 0xe400000
	s_addc_u32 s5, s57, 0
	v_lshlrev_b32_e32 v3, 3, v1
	s_lshl_b32 s8, s2, 3
	s_mov_b64 s[6:7], 0
	v_mov_b32_e32 v5, 0
	s_mov_b32 s9, 0x1ffff
	v_mov_b32_e32 v6, v1
